# phase prologues: the vmcnt(0) hipcc puts after the first row-scale/residual flat_load moved to its first consumer
# baseline (speedup 1.0000x reference)
.LBB0_206:
	s_andn2_b64 vcc, exec, s[4:5]
	s_cbranch_vccnz .LBB0_338
	v_ashrrev_i32_e32 v3, 31, v1
	v_lshrrev_b32_e32 v3, 26, v3
	v_add_u32_e32 v3, v1, v3
	v_ashrrev_i32_e32 v12, 6, v3
	v_bfe_i32 v3, v1, 27, 1
	v_lshlrev_b32_e32 v2, 4, v1
	v_lshrrev_b32_e32 v3, 22, v3
	v_add_u32_e32 v3, v2, v3
	v_and_b32_e32 v3, 0xfffffc00, v3
	v_sub_u32_e32 v3, v2, v3
	v_lshrrev_b32_e32 v4, 4, v3
	v_bitop3_b32 v3, v4, v3, 32 bitop3:0x6c
	v_ashrrev_i32_e32 v5, 31, v3
	v_lshrrev_b32_e32 v5, 26, v5
	v_add_u32_e32 v5, v3, v5
	v_lshlrev_b32_e32 v4, 3, v12
	v_ashrrev_i32_e32 v13, 6, v5
	v_and_b32_e32 v5, 0xc0, v5
	v_and_b32_e32 v4, -16, v4
	v_sub_u32_e32 v3, v3, v5
	v_mov_b32_e32 v5, 1
	v_add_u32_e32 v4, v13, v4
	v_ashrrev_i16_sdwa v3, v5, sext(v3) dst_sel:DWORD dst_unused:UNUSED_PAD src0_sel:DWORD src1_sel:BYTE_0
	v_lshlrev_b32_e32 v6, 5, v12
	v_bfe_i32 v15, v3, 0, 16
	v_lshlrev_b32_e32 v3, 1, v4
	v_lshrrev_b32_e32 v7, 2, v4
	v_and_b32_e32 v8, 3, v13
	s_mov_b32 s1, 0x1fffe0
	v_and_b32_e32 v6, 32, v6
	v_and_b32_e32 v3, 24, v3
	v_and_b32_e32 v7, 4, v7
	v_and_or_b32 v8, v4, s1, v8
	v_or3_b32 v3, v8, v7, v3
	v_add_lshl_u32 v6, v6, v15, 1
	v_add_u32_e32 v2, 0x2000, v2
	v_lshl_add_u32 v132, v3, 11, v6
	v_ashrrev_i32_e32 v3, 31, v2
	v_lshrrev_b32_e32 v3, 22, v3
	v_add_u32_e32 v3, v2, v3
	v_ashrrev_i32_e32 v16, 10, v3
	v_mul_i32_i24_e32 v3, 0x400, v16
	v_sub_u32_e32 v2, v2, v3
	v_lshrrev_b32_e32 v3, 4, v2
	v_bitop3_b32 v2, v3, v2, 32 bitop3:0x6c
	v_lshl_add_u32 v130, v4, 11, v6
	v_ashrrev_i32_e32 v4, 31, v2
	v_lshrrev_b32_e32 v4, 26, v4
	v_add_u32_e32 v4, v2, v4
	s_add_u32 s40, s2, 0x4c00000
	v_lshlrev_b32_e32 v3, 3, v16
	v_ashrrev_i32_e32 v17, 6, v4
	v_and_b32_e32 v4, 0xc0, v4
	s_addc_u32 s41, s3, 0
	v_and_b32_e32 v3, -16, v3
	v_sub_u32_e32 v2, v2, v4
	s_add_u32 s42, s2, 0x900000
	v_add_u32_e32 v3, v17, v3
	v_ashrrev_i16_sdwa v2, v5, sext(v2) dst_sel:DWORD dst_unused:UNUSED_PAD src0_sel:DWORD src1_sel:BYTE_0
	v_and_b32_e32 v5, 3, v17
	s_addc_u32 s43, s3, 0
	s_ashr_i32 s4, s6, 6
	v_and_or_b32 v5, v3, s1, v5
	s_ashr_i32 s7, s6, 8
	s_ashr_i32 s9, s8, 31
	s_ashr_i32 s1, s0, 31
	s_lshl_b32 s44, s4, 10
	s_lshl_b32 s5, s7, 6
	s_lshl_b64 s[10:11], s[8:9], 19
	s_lshl_b64 s[12:13], s[0:1], 19
	s_add_u32 s34, s42, s12
	v_lshlrev_b32_e32 v6, 5, v16
	v_bfe_i32 v18, v2, 0, 16
	v_lshlrev_b32_e32 v2, 1, v3
	v_lshrrev_b32_e32 v4, 2, v3
	s_addc_u32 s35, s43, s13
	s_add_i32 s45, s44, 0
	v_and_b32_e32 v6, 32, v6
	v_and_b32_e32 v2, 24, v2
	v_and_b32_e32 v4, 4, v4
	s_add_i32 m0, s45, 0x10000
	v_or3_b32 v2, v5, v4, v2
	v_add_lshl_u32 v4, v6, v18, 1
	global_load_lds_dwordx4 v132, s[34:35]
	s_add_i32 m0, s45, 0x12000
	v_lshl_add_u32 v136, v2, 11, v4
	s_add_u32 s12, s34, 0x40000
	global_load_lds_dwordx4 v136, s[34:35]
	s_addc_u32 s13, s35, 0
	s_add_i32 m0, s45, 0x14000
	v_lshl_add_u32 v134, v3, 11, v4
	global_load_lds_dwordx4 v132, s[12:13]
	s_add_i32 m0, s45, 0x16000
	s_add_u32 s36, s40, s10
	s_addc_u32 s37, s41, s11
	s_add_i32 s46, s45, 0x2000
	s_add_u32 s10, s36, 0x40000
	global_load_lds_dwordx4 v136, s[12:13]
	s_mov_b32 m0, s45
	s_addc_u32 s11, s37, 0
	s_lshl_b32 s1, s8, 8
	v_and_b32_e32 v19, 15, v1
	global_load_lds_dwordx4 v130, s[36:37]
	s_mov_b32 m0, s46
	s_add_i32 s47, s45, 0x4000
	s_add_i32 s1, s1, s5
	v_bfe_u32 v14, v1, 4, 2
	v_mov_b32_e32 v133, 0
	global_load_lds_dwordx4 v134, s[36:37]
	s_mov_b32 m0, s47
	s_add_i32 s48, s45, 0x6000
	v_or_b32_e32 v4, s1, v19
	global_load_lds_dwordx4 v130, s[10:11]
	s_mov_b32 m0, s48
	v_lshlrev_b32_e32 v2, 4, v14
	v_mov_b32_e32 v3, v133
	v_or_b32_e32 v8, 16, v4
	global_load_lds_dwordx4 v134, s[10:11]
	v_lshl_add_u64 v[6:7], s[2:3], 0, v[2:3]
	s_mov_b64 s[10:11], 0x100000
	v_ashrrev_i32_e32 v5, 31, v4
	v_ashrrev_i32_e32 v9, 31, v8
	v_lshl_add_u64 v[138:139], v[6:7], 0, s[10:11]
	v_lshlrev_b64 v[6:7], 6, v[4:5]
	v_lshlrev_b64 v[8:9], 6, v[8:9]
	v_lshl_add_u64 v[6:7], v[138:139], 0, v[6:7]
	v_lshl_add_u64 v[8:9], v[138:139], 0, v[8:9]
	flat_load_dwordx4 v[20:23], v[6:7]
	flat_load_dwordx4 v[24:27], v[8:9]
	v_or_b32_e32 v8, 32, v4
	v_or_b32_e32 v4, 48, v4
	v_ashrrev_i32_e32 v5, 31, v4
	v_ashrrev_i32_e32 v9, 31, v8
	v_lshlrev_b64 v[4:5], 6, v[4:5]
	v_lshlrev_b64 v[8:9], 6, v[8:9]
	v_lshl_add_u64 v[4:5], v[138:139], 0, v[4:5]
	v_lshl_add_u64 v[8:9], v[138:139], 0, v[8:9]
	flat_load_dwordx4 v[32:35], v[4:5]
	s_movk_i32 s49, 0x2000
	flat_load_dwordx4 v[28:31], v[8:9]
	v_add_co_u32_e32 v4, vcc, s49, v6
	v_mbcnt_lo_u32_b32 v1, -1, 0
	s_nop 0
	v_addc_co_u32_e32 v5, vcc, 0, v7, vcc
	flat_load_dwordx4 v[36:39], v[4:5]
	flat_load_dwordx4 v[40:43], v[4:5] offset:1024
	flat_load_dwordx4 v[44:47], v[4:5] offset:2048
	flat_load_dwordx4 v[48:51], v[4:5] offset:3072
	v_mbcnt_hi_u32_b32 v3, -1, v1
	v_and_b32_e32 v52, 64, v3
	v_xor_b32_e32 v1, 16, v3
	v_add_u32_e32 v52, 64, v52
	v_cmp_lt_i32_e32 vcc, v1, v52
	v_xor_b32_e32 v53, 32, v3
	v_mov_b32_e32 v137, v133
	v_cndmask_b32_e32 v1, v3, v1, vcc
	v_lshlrev_b32_e32 v1, 2, v1
	v_cmp_lt_i32_e32 vcc, v53, v52
	v_mov_b32_e32 v131, v133
	v_mov_b32_e32 v135, v133
	v_cndmask_b32_e32 v3, v3, v53, vcc
	v_lshlrev_b32_e32 v168, 2, v3
	s_cmp_eq_u32 s7, 1
	v_lshl_add_u64 v[10:11], s[34:35], 0, v[132:133]
	v_lshl_add_u64 v[8:9], s[34:35], 0, v[136:137]
	v_lshl_add_u64 v[6:7], s[36:37], 0, v[130:131]
	v_lshl_add_u64 v[4:5], s[36:37], 0, v[134:135]
	s_cselect_b64 s[10:11], -1, 0
	s_cmp_lg_u32 s7, 1
	s_mov_b32 s13, 0
	s_waitcnt lgkmcnt(0)
	s_waitcnt vmcnt(0)
	v_add_f32_e32 v20, v20, v21
	v_add_f32_e32 v21, v22, v23
	s_waitcnt vmcnt(0)
	v_add_f32_e32 v22, v24, v25
	v_add_f32_e32 v23, v26, v27
	v_add_f32_e32 v23, v22, v23
	ds_bpermute_b32 v24, v1, v23
	v_add_f32_e32 v20, v20, v21
	ds_bpermute_b32 v21, v1, v20
	v_add_f32_e32 v25, v32, v33
	v_add_f32_e32 v26, v34, v35
	s_waitcnt lgkmcnt(1)
	v_add_f32_e32 v3, v23, v24
	v_add_f32_e32 v23, v28, v29
	v_add_f32_e32 v24, v30, v31
	v_add_f32_e32 v25, v25, v26
	v_add_f32_e32 v26, v36, v37
	v_add_f32_e32 v28, v38, v39
	v_add_f32_e32 v23, v23, v24
	v_add_f32_e32 v29, v26, v28
	ds_bpermute_b32 v24, v1, v23
	ds_bpermute_b32 v30, v1, v29
	v_add_f32_e32 v31, v44, v45
	v_add_f32_e32 v32, v46, v47
	v_add_f32_e32 v31, v31, v32
	s_waitcnt lgkmcnt(1)
	v_add_f32_e32 v26, v23, v24
	s_waitcnt lgkmcnt(0)
	v_add_f32_e32 v23, v29, v30
	v_add_f32_e32 v29, v40, v41
	v_add_f32_e32 v30, v42, v43
	v_add_f32_e32 v32, v48, v49
	v_add_f32_e32 v34, v50, v51
	v_add_f32_e32 v29, v29, v30
	v_add_f32_e32 v35, v32, v34
	ds_bpermute_b32 v27, v1, v25
	ds_bpermute_b32 v30, v1, v29
	ds_bpermute_b32 v33, v1, v31
	ds_bpermute_b32 v36, v1, v35
	v_add_f32_e32 v21, v20, v21
	s_waitcnt lgkmcnt(3)
	v_add_f32_e32 v24, v25, v27
	s_waitcnt lgkmcnt(2)
	v_add_f32_e32 v32, v29, v30
	s_waitcnt lgkmcnt(1)
	v_add_f32_e32 v30, v31, v33
	s_waitcnt lgkmcnt(0)
	v_add_f32_e32 v29, v35, v36
	ds_bpermute_b32 v22, v168, v21
	ds_bpermute_b32 v20, v168, v3
	ds_bpermute_b32 v28, v168, v26
	ds_bpermute_b32 v27, v168, v24
	ds_bpermute_b32 v25, v168, v23
	ds_bpermute_b32 v34, v168, v32
	ds_bpermute_b32 v33, v168, v30
	ds_bpermute_b32 v31, v168, v29
	s_cbranch_scc1 .LBB0_209
	s_barrier

.LBB0_668:
	s_andn2_b64 vcc, exec, s[0:1]
	s_cbranch_vccnz .LBB0_768
	v_ashrrev_i32_e32 v3, 31, v1
	v_lshrrev_b32_e32 v3, 26, v3
	v_add_u32_e32 v3, v1, v3
	v_ashrrev_i32_e32 v146, 6, v3
	v_bfe_i32 v3, v1, 27, 1
	v_lshlrev_b32_e32 v2, 4, v1
	v_lshrrev_b32_e32 v3, 22, v3
	v_add_u32_e32 v3, v2, v3
	v_and_b32_e32 v3, 0xfffffc00, v3
	v_sub_u32_e32 v3, v2, v3
	v_lshrrev_b32_e32 v4, 4, v3
	v_bitop3_b32 v3, v4, v3, 32 bitop3:0x6c
	v_ashrrev_i32_e32 v5, 31, v3
	v_lshrrev_b32_e32 v5, 26, v5
	v_add_u32_e32 v5, v3, v5
	v_lshlrev_b32_e32 v4, 3, v146
	v_ashrrev_i32_e32 v147, 6, v5
	v_and_b32_e32 v5, 0xc0, v5
	v_and_b32_e32 v4, -16, v4
	v_sub_u32_e32 v3, v3, v5
	v_mov_b32_e32 v5, 1
	v_add_u32_e32 v4, v147, v4
	v_ashrrev_i16_sdwa v3, v5, sext(v3) dst_sel:DWORD dst_unused:UNUSED_PAD src0_sel:DWORD src1_sel:BYTE_0
	v_lshlrev_b32_e32 v6, 5, v146
	v_bfe_i32 v149, v3, 0, 16
	v_lshlrev_b32_e32 v3, 1, v4
	v_lshrrev_b32_e32 v7, 2, v4
	v_and_b32_e32 v8, 3, v147
	s_mov_b32 s5, 0x1fffe0
	v_and_b32_e32 v6, 32, v6
	v_and_b32_e32 v3, 24, v3
	v_and_b32_e32 v7, 4, v7
	v_and_or_b32 v8, v4, s5, v8
	v_or3_b32 v3, v8, v7, v3
	v_add_lshl_u32 v6, v6, v149, 1
	v_add_u32_e32 v2, 0x2000, v2
	v_lshl_add_u32 v136, v3, 11, v6
	v_ashrrev_i32_e32 v3, 31, v2
	v_lshrrev_b32_e32 v3, 22, v3
	v_add_u32_e32 v3, v2, v3
	v_ashrrev_i32_e32 v150, 10, v3
	v_mul_i32_i24_e32 v3, 0x400, v150
	v_sub_u32_e32 v2, v2, v3
	v_lshrrev_b32_e32 v3, 4, v2
	s_add_u32 s0, s2, 0x4c00000
	v_bitop3_b32 v2, v3, v2, 32 bitop3:0x6c
	s_addc_u32 s1, s3, 0
	v_lshl_add_u32 v134, v4, 11, v6
	v_ashrrev_i32_e32 v4, 31, v2
	s_add_u32 s33, s2, 0xac00000
	v_lshrrev_b32_e32 v4, 26, v4
	s_addc_u32 s46, s3, 0
	v_add_u32_e32 v4, v2, v4
	s_add_u32 s47, s2, 0xd00000
	v_lshlrev_b32_e32 v3, 3, v150
	v_ashrrev_i32_e32 v151, 6, v4
	v_and_b32_e32 v4, 0xc0, v4
	s_addc_u32 s48, s3, 0
	s_ashr_i32 s4, s6, 6
	v_and_b32_e32 v3, -16, v3
	v_sub_u32_e32 v2, v2, v4
	s_and_b32 s49, s4, 3
	v_add_u32_e32 v3, v151, v3
	v_ashrrev_i16_sdwa v2, v5, sext(v2) dst_sel:DWORD dst_unused:UNUSED_PAD src0_sel:DWORD src1_sel:BYTE_0
	v_and_b32_e32 v5, 3, v151
	s_ashr_i32 s7, s6, 8
	s_ashr_i32 s39, s38, 31
	s_ashr_i32 s19, s18, 31
	v_and_or_b32 v5, v3, s5, v5
	s_lshl_b32 s50, s4, 10
	s_lshl_b32 s5, s7, 6
	s_lshl_b32 s4, s49, 5
	s_lshl_b64 s[10:11], s[38:39], 19
	s_lshl_b64 s[8:9], s[18:19], 19
	s_add_u32 s40, s47, s8
	v_lshlrev_b32_e32 v6, 5, v150
	v_bfe_i32 v152, v2, 0, 16
	v_lshlrev_b32_e32 v2, 1, v3
	v_lshrrev_b32_e32 v4, 2, v3
	s_addc_u32 s41, s48, s9
	s_add_i32 s51, s50, 0
	v_and_b32_e32 v6, 32, v6
	v_and_b32_e32 v2, 24, v2
	v_and_b32_e32 v4, 4, v4
	s_add_i32 m0, s51, 0x10000
	v_or3_b32 v2, v5, v4, v2
	v_add_lshl_u32 v4, v6, v152, 1
	global_load_lds_dwordx4 v136, s[40:41]
	s_add_i32 m0, s51, 0x12000
	v_lshl_add_u32 v140, v2, 11, v4
	s_add_u32 s12, s40, 0x40000
	global_load_lds_dwordx4 v140, s[40:41]
	s_addc_u32 s13, s41, 0
	s_add_i32 m0, s51, 0x14000
	v_lshl_add_u32 v138, v3, 11, v4
	global_load_lds_dwordx4 v136, s[12:13]
	s_add_i32 m0, s51, 0x16000
	s_add_u32 s42, s33, s10
	s_addc_u32 s43, s46, s11
	s_add_i32 s52, s51, 0x2000
	global_load_lds_dwordx4 v140, s[12:13]
	s_mov_b32 m0, s51
	s_add_u32 s10, s42, 0x40000
	global_load_lds_dwordx4 v134, s[42:43]
	s_mov_b32 m0, s52
	s_addc_u32 s11, s43, 0
	s_add_i32 s53, s51, 0x4000
	global_load_lds_dwordx4 v138, s[42:43]
	s_mov_b32 m0, s53
	s_add_i32 s54, s51, 0x6000
	global_load_lds_dwordx4 v134, s[10:11]
	s_mov_b32 m0, s54
	v_and_b32_e32 v154, 15, v1
	global_load_lds_dwordx4 v138, s[10:11]
	s_lshl_b32 s10, s38, 8
	s_add_i32 s10, s10, s5
	v_bfe_u32 v148, v1, 4, 2
	v_or_b32_e32 v2, s10, v154
	s_lshl_b32 s10, s18, 8
	v_lshlrev_b32_e32 v153, 3, v148
	s_or_b32 s10, s10, s4
	v_or_b32_e32 v4, s10, v153
	v_or_b32_e32 v8, 16, v2
	v_ashrrev_i32_e32 v5, 31, v4
	v_ashrrev_i32_e32 v3, 31, v2
	v_ashrrev_i32_e32 v9, 31, v8
	v_lshl_add_u64 v[4:5], v[4:5], 1, s[0:1]
	v_lshlrev_b64 v[6:7], 11, v[2:3]
	v_lshlrev_b64 v[8:9], 11, v[8:9]
	v_lshl_add_u64 v[6:7], v[4:5], 0, v[6:7]
	v_lshl_add_u64 v[8:9], v[4:5], 0, v[8:9]
	flat_load_dwordx4 v[62:65], v[6:7]
	flat_load_dwordx4 v[58:61], v[6:7] offset:256
	flat_load_dwordx4 v[54:57], v[8:9]
	flat_load_dwordx4 v[46:49], v[8:9] offset:256
	v_or_b32_e32 v8, 32, v2
	v_or_b32_e32 v2, 48, v2
	v_ashrrev_i32_e32 v9, 31, v8
	v_ashrrev_i32_e32 v3, 31, v2
	v_lshlrev_b64 v[8:9], 11, v[8:9]
	v_lshlrev_b64 v[2:3], 11, v[2:3]
	s_mov_b32 s55, 0x40000
	v_lshl_add_u64 v[8:9], v[4:5], 0, v[8:9]
	v_lshl_add_u64 v[2:3], v[4:5], 0, v[2:3]
	v_add_co_u32_e32 v4, vcc, s55, v6
	s_mov_b64 s[8:9], 0x40000
	s_nop 0
	v_addc_co_u32_e32 v5, vcc, 0, v7, vcc
	s_mov_b32 s56, 0x48000
	flat_load_dwordx4 v[50:53], v[8:9]
	flat_load_dwordx4 v[38:41], v[8:9] offset:256
	flat_load_dwordx4 v[42:45], v[2:3]
	flat_load_dwordx4 v[26:29], v[2:3] offset:256
	v_lshl_add_u64 v[2:3], v[6:7], 0, s[8:9]
	flat_load_dwordx4 v[34:37], v[4:5]
	flat_load_dwordx4 v[18:21], v[2:3] offset:256
	v_add_co_u32_e32 v4, vcc, s56, v6
	s_mov_b64 s[10:11], 0x48000
	s_nop 0
	v_addc_co_u32_e32 v5, vcc, 0, v7, vcc
	s_mov_b32 s14, 0x50000
	v_lshl_add_u64 v[2:3], v[6:7], 0, s[10:11]
	flat_load_dwordx4 v[30:33], v[4:5]
	flat_load_dwordx4 v[10:13], v[2:3] offset:256
	v_add_co_u32_e32 v4, vcc, s14, v6
	s_mov_b64 s[12:13], 0x50000
	s_nop 0
	v_addc_co_u32_e32 v5, vcc, 0, v7, vcc
	s_mov_b64 s[14:15], 0x58000
	s_mov_b32 s16, 0x58000
	v_lshl_add_u64 v[2:3], v[6:7], 0, s[12:13]
	v_lshl_add_u64 v[14:15], v[6:7], 0, s[14:15]
	v_add_co_u32_e32 v6, vcc, s16, v6
	flat_load_dwordx4 v[22:25], v[4:5]
	s_nop 0
	flat_load_dwordx4 v[2:5], v[2:3] offset:256
	v_addc_co_u32_e32 v7, vcc, 0, v7, vcc
	flat_load_dwordx4 v[6:9], v[6:7]
	s_nop 0
	flat_load_dwordx4 v[14:17], v[14:15] offset:256
	v_mov_b32_e32 v137, 0
	v_mov_b32_e32 v141, v137
	v_mov_b32_e32 v135, v137
	v_mov_b32_e32 v139, v137
	s_cmp_eq_u32 s7, 1
	v_lshl_add_u64 v[144:145], s[40:41], 0, v[136:137]
	v_lshl_add_u64 v[142:143], s[40:41], 0, v[140:141]
	v_lshl_add_u64 v[132:133], s[42:43], 0, v[134:135]
	v_lshl_add_u64 v[130:131], s[42:43], 0, v[138:139]
	s_cselect_b64 s[16:17], -1, 0
	s_cmp_lg_u32 s7, 1
	s_mov_b32 s19, 0
	s_waitcnt vmcnt(0)
	s_cbranch_scc1 .LBB0_671
	s_barrier

.LBB0_845:
	s_andn2_b64 vcc, exec, s[0:1]
	s_cbranch_vccnz .LBB0_929
	v_ashrrev_i32_e32 v3, 31, v1
	v_lshrrev_b32_e32 v3, 26, v3
	v_add_u32_e32 v3, v1, v3
	v_ashrrev_i32_e32 v12, 6, v3
	v_bfe_i32 v3, v1, 27, 1
	v_lshlrev_b32_e32 v2, 4, v1
	v_lshrrev_b32_e32 v3, 22, v3
	v_add_u32_e32 v3, v2, v3
	v_and_b32_e32 v3, 0xfffffc00, v3
	v_sub_u32_e32 v3, v2, v3
	v_lshrrev_b32_e32 v4, 4, v3
	v_bitop3_b32 v3, v4, v3, 32 bitop3:0x6c
	v_ashrrev_i32_e32 v5, 31, v3
	v_lshrrev_b32_e32 v5, 26, v5
	v_add_u32_e32 v5, v3, v5
	v_lshlrev_b32_e32 v4, 3, v12
	v_ashrrev_i32_e32 v13, 6, v5
	v_and_b32_e32 v5, 0xc0, v5
	v_and_b32_e32 v4, -16, v4
	v_sub_u32_e32 v3, v3, v5
	v_mov_b32_e32 v5, 1
	v_add_u32_e32 v4, v13, v4
	v_ashrrev_i16_sdwa v3, v5, sext(v3) dst_sel:DWORD dst_unused:UNUSED_PAD src0_sel:DWORD src1_sel:BYTE_0
	v_lshlrev_b32_e32 v6, 5, v12
	v_bfe_i32 v14, v3, 0, 16
	v_lshlrev_b32_e32 v3, 1, v4
	v_lshrrev_b32_e32 v7, 2, v4
	v_and_b32_e32 v8, 3, v13
	s_mov_b32 s0, 0x1fffe0
	v_and_b32_e32 v6, 32, v6
	v_and_b32_e32 v3, 24, v3
	v_and_b32_e32 v7, 4, v7
	v_and_or_b32 v8, v4, s0, v8
	v_or3_b32 v3, v8, v7, v3
	v_add_lshl_u32 v6, v6, v14, 1
	v_add_u32_e32 v2, 0x2000, v2
	v_lshl_add_u32 v132, v3, 11, v6
	v_ashrrev_i32_e32 v3, 31, v2
	v_lshrrev_b32_e32 v3, 22, v3
	v_add_u32_e32 v3, v2, v3
	v_ashrrev_i32_e32 v16, 10, v3
	v_mul_i32_i24_e32 v3, 0x400, v16
	v_sub_u32_e32 v2, v2, v3
	v_lshrrev_b32_e32 v3, 4, v2
	v_bitop3_b32 v2, v3, v2, 32 bitop3:0x6c
	v_lshl_add_u32 v130, v4, 11, v6
	v_ashrrev_i32_e32 v4, 31, v2
	v_lshrrev_b32_e32 v4, 26, v4
	s_add_u32 s33, s2, 0x4c00000
	v_add_u32_e32 v4, v2, v4
	s_addc_u32 s42, s3, 0
	v_lshlrev_b32_e32 v3, 3, v16
	v_ashrrev_i32_e32 v17, 6, v4
	v_and_b32_e32 v4, 0xc0, v4
	s_add_u32 s43, s2, 0x1700000
	v_and_b32_e32 v3, -16, v3
	v_sub_u32_e32 v2, v2, v4
	s_addc_u32 s44, s3, 0
	s_ashr_i32 s4, s10, 6
	v_add_u32_e32 v3, v17, v3
	v_ashrrev_i16_sdwa v2, v5, sext(v2) dst_sel:DWORD dst_unused:UNUSED_PAD src0_sel:DWORD src1_sel:BYTE_0
	v_and_b32_e32 v5, 3, v17
	s_ashr_i32 s8, s10, 8
	s_ashr_i32 s31, s30, 31
	s_ashr_i32 s35, s34, 31
	v_and_or_b32 v5, v3, s0, v5
	s_lshl_b32 s45, s4, 10
	s_lshl_b32 s5, s8, 6
	s_lshl_b64 s[0:1], s[30:31], 19
	s_lshl_b64 s[6:7], s[34:35], 19
	s_add_u32 s36, s43, s6
	v_lshlrev_b32_e32 v6, 5, v16
	v_bfe_i32 v18, v2, 0, 16
	v_lshlrev_b32_e32 v2, 1, v3
	v_lshrrev_b32_e32 v4, 2, v3
	s_addc_u32 s37, s44, s7
	s_add_i32 s35, s45, 0
	v_and_b32_e32 v6, 32, v6
	v_and_b32_e32 v2, 24, v2
	v_and_b32_e32 v4, 4, v4
	s_add_i32 m0, s35, 0x10000
	v_or3_b32 v2, v5, v4, v2
	v_add_lshl_u32 v4, v6, v18, 1
	global_load_lds_dwordx4 v132, s[36:37]
	s_add_i32 m0, s35, 0x12000
	v_lshl_add_u32 v136, v2, 11, v4
	s_add_u32 s6, s36, 0x40000
	global_load_lds_dwordx4 v136, s[36:37]
	s_addc_u32 s7, s37, 0
	s_add_i32 m0, s35, 0x14000
	v_lshl_add_u32 v134, v3, 11, v4
	global_load_lds_dwordx4 v132, s[6:7]
	s_add_i32 m0, s35, 0x16000
	s_add_u32 s38, s33, s0
	s_addc_u32 s39, s42, s1
	s_add_i32 s46, s35, 0x2000
	global_load_lds_dwordx4 v136, s[6:7]
	s_mov_b32 m0, s35
	s_add_u32 s0, s38, 0x40000
	global_load_lds_dwordx4 v130, s[38:39]
	s_mov_b32 m0, s46
	s_addc_u32 s1, s39, 0
	s_add_i32 s47, s35, 0x4000
	global_load_lds_dwordx4 v134, s[38:39]
	s_mov_b32 m0, s47
	s_add_i32 s48, s35, 0x6000
	global_load_lds_dwordx4 v130, s[0:1]
	s_mov_b32 m0, s48
	v_and_b32_e32 v19, 15, v1
	global_load_lds_dwordx4 v134, s[0:1]
	s_lshl_b32 s0, s30, 8
	s_add_i32 s0, s0, s5
	v_bfe_u32 v15, v1, 4, 2
	v_mov_b32_e32 v133, 0
	v_or_b32_e32 v4, s0, v19
	v_lshlrev_b32_e32 v2, 4, v15
	v_mov_b32_e32 v3, v133
	v_or_b32_e32 v8, 16, v4
	v_lshl_add_u64 v[6:7], s[2:3], 0, v[2:3]
	s_mov_b64 s[0:1], 0x300000
	v_ashrrev_i32_e32 v5, 31, v4
	v_ashrrev_i32_e32 v9, 31, v8
	v_lshl_add_u64 v[138:139], v[6:7], 0, s[0:1]
	v_lshlrev_b64 v[6:7], 6, v[4:5]
	v_lshlrev_b64 v[8:9], 6, v[8:9]
	v_lshl_add_u64 v[6:7], v[138:139], 0, v[6:7]
	v_lshl_add_u64 v[8:9], v[138:139], 0, v[8:9]
	flat_load_dwordx4 v[20:23], v[6:7]
	flat_load_dwordx4 v[24:27], v[8:9]
	v_or_b32_e32 v8, 32, v4
	v_or_b32_e32 v4, 48, v4
	v_ashrrev_i32_e32 v5, 31, v4
	v_ashrrev_i32_e32 v9, 31, v8
	v_lshlrev_b64 v[4:5], 6, v[4:5]
	v_lshlrev_b64 v[8:9], 6, v[8:9]
	v_lshl_add_u64 v[4:5], v[138:139], 0, v[4:5]
	v_lshl_add_u64 v[8:9], v[138:139], 0, v[8:9]
	flat_load_dwordx4 v[32:35], v[4:5]
	s_movk_i32 s49, 0x2000
	flat_load_dwordx4 v[28:31], v[8:9]
	v_add_co_u32_e32 v4, vcc, s49, v6
	v_mbcnt_lo_u32_b32 v1, -1, 0
	s_nop 0
	v_addc_co_u32_e32 v5, vcc, 0, v7, vcc
	flat_load_dwordx4 v[36:39], v[4:5]
	flat_load_dwordx4 v[40:43], v[4:5] offset:1024
	flat_load_dwordx4 v[44:47], v[4:5] offset:2048
	flat_load_dwordx4 v[48:51], v[4:5] offset:3072
	v_mbcnt_hi_u32_b32 v3, -1, v1
	v_and_b32_e32 v52, 64, v3
	v_xor_b32_e32 v1, 16, v3
	v_add_u32_e32 v52, 64, v52
	v_cmp_lt_i32_e32 vcc, v1, v52
	v_xor_b32_e32 v53, 32, v3
	v_mov_b32_e32 v137, v133
	v_cndmask_b32_e32 v1, v3, v1, vcc
	v_lshlrev_b32_e32 v1, 2, v1
	v_cmp_lt_i32_e32 vcc, v53, v52
	v_mov_b32_e32 v131, v133
	v_mov_b32_e32 v135, v133
	v_cndmask_b32_e32 v3, v3, v53, vcc
	v_lshlrev_b32_e32 v168, 2, v3
	s_cmp_eq_u32 s8, 1
	v_lshl_add_u64 v[10:11], s[36:37], 0, v[132:133]
	v_lshl_add_u64 v[8:9], s[36:37], 0, v[136:137]
	v_lshl_add_u64 v[6:7], s[38:39], 0, v[130:131]
	v_lshl_add_u64 v[4:5], s[38:39], 0, v[134:135]
	s_cselect_b64 s[0:1], -1, 0
	s_cmp_lg_u32 s8, 1
	s_mov_b32 s50, 0
	s_waitcnt lgkmcnt(0)
	s_waitcnt vmcnt(0)
	v_add_f32_e32 v20, v20, v21
	v_add_f32_e32 v21, v22, v23
	s_waitcnt vmcnt(0)
	v_add_f32_e32 v22, v24, v25
	v_add_f32_e32 v23, v26, v27
	v_add_f32_e32 v23, v22, v23
	ds_bpermute_b32 v24, v1, v23
	v_add_f32_e32 v20, v20, v21
	ds_bpermute_b32 v21, v1, v20
	v_add_f32_e32 v25, v32, v33
	v_add_f32_e32 v26, v34, v35
	s_waitcnt lgkmcnt(1)
	v_add_f32_e32 v3, v23, v24
	v_add_f32_e32 v23, v28, v29
	v_add_f32_e32 v24, v30, v31
	v_add_f32_e32 v25, v25, v26
	v_add_f32_e32 v26, v36, v37
	v_add_f32_e32 v28, v38, v39
	v_add_f32_e32 v23, v23, v24
	v_add_f32_e32 v29, v26, v28
	ds_bpermute_b32 v24, v1, v23
	ds_bpermute_b32 v30, v1, v29
	v_add_f32_e32 v31, v44, v45
	v_add_f32_e32 v32, v46, v47
	v_add_f32_e32 v31, v31, v32
	s_waitcnt lgkmcnt(1)
	v_add_f32_e32 v26, v23, v24
	s_waitcnt lgkmcnt(0)
	v_add_f32_e32 v23, v29, v30
	v_add_f32_e32 v29, v40, v41
	v_add_f32_e32 v30, v42, v43
	v_add_f32_e32 v32, v48, v49
	v_add_f32_e32 v34, v50, v51
	v_add_f32_e32 v29, v29, v30
	v_add_f32_e32 v35, v32, v34
	ds_bpermute_b32 v27, v1, v25
	ds_bpermute_b32 v30, v1, v29
	ds_bpermute_b32 v33, v1, v31
	ds_bpermute_b32 v36, v1, v35
	v_add_f32_e32 v21, v20, v21
	s_waitcnt lgkmcnt(3)
	v_add_f32_e32 v24, v25, v27
	s_waitcnt lgkmcnt(2)
	v_add_f32_e32 v32, v29, v30
	s_waitcnt lgkmcnt(1)
	v_add_f32_e32 v30, v31, v33
	s_waitcnt lgkmcnt(0)
	v_add_f32_e32 v29, v35, v36
	ds_bpermute_b32 v22, v168, v21
	ds_bpermute_b32 v20, v168, v3
	ds_bpermute_b32 v28, v168, v26
	ds_bpermute_b32 v27, v168, v24
	ds_bpermute_b32 v25, v168, v23
	ds_bpermute_b32 v34, v168, v32
	ds_bpermute_b32 v33, v168, v30
	ds_bpermute_b32 v31, v168, v29
	s_cbranch_scc1 .LBB0_848
	s_barrier

.LBB0_1026:
	s_andn2_b64 vcc, exec, s[0:1]
	s_cbranch_vccnz .LBB0_1126
	v_ashrrev_i32_e32 v3, 31, v1
	v_lshrrev_b32_e32 v3, 26, v3
	v_add_u32_e32 v3, v1, v3
	v_ashrrev_i32_e32 v146, 6, v3
	v_bfe_i32 v3, v1, 27, 1
	v_lshlrev_b32_e32 v2, 4, v1
	v_lshrrev_b32_e32 v3, 22, v3
	v_add_u32_e32 v3, v2, v3
	v_and_b32_e32 v3, 0xfffffc00, v3
	v_sub_u32_e32 v3, v2, v3
	v_lshrrev_b32_e32 v4, 4, v3
	v_bitop3_b32 v3, v4, v3, 32 bitop3:0x6c
	v_ashrrev_i32_e32 v5, 31, v3
	v_lshrrev_b32_e32 v5, 26, v5
	v_add_u32_e32 v5, v3, v5
	v_lshlrev_b32_e32 v4, 3, v146
	v_ashrrev_i32_e32 v147, 6, v5
	v_and_b32_e32 v5, 0xc0, v5
	v_and_b32_e32 v4, -16, v4
	v_sub_u32_e32 v3, v3, v5
	v_mov_b32_e32 v5, 1
	v_add_u32_e32 v4, v147, v4
	v_ashrrev_i16_sdwa v3, v5, sext(v3) dst_sel:DWORD dst_unused:UNUSED_PAD src0_sel:DWORD src1_sel:BYTE_0
	v_lshlrev_b32_e32 v6, 5, v146
	v_bfe_i32 v149, v3, 0, 16
	v_lshlrev_b32_e32 v3, 1, v4
	v_lshrrev_b32_e32 v7, 2, v4
	v_and_b32_e32 v8, 3, v147
	s_mov_b32 s5, 0x7ffe0
	v_and_b32_e32 v6, 32, v6
	v_and_b32_e32 v3, 24, v3
	v_and_b32_e32 v7, 4, v7
	v_and_or_b32 v8, v4, s5, v8
	v_or3_b32 v3, v8, v7, v3
	v_add_lshl_u32 v6, v6, v149, 1
	v_add_u32_e32 v2, 0x2000, v2
	v_lshl_add_u32 v136, v3, 13, v6
	v_ashrrev_i32_e32 v3, 31, v2
	v_lshrrev_b32_e32 v3, 22, v3
	v_add_u32_e32 v3, v2, v3
	v_ashrrev_i32_e32 v150, 10, v3
	v_mul_i32_i24_e32 v3, 0x400, v150
	v_sub_u32_e32 v2, v2, v3
	v_lshrrev_b32_e32 v3, 4, v2
	s_add_u32 s0, s2, 0x4c00000
	v_bitop3_b32 v2, v3, v2, 32 bitop3:0x6c
	s_addc_u32 s1, s3, 0
	v_lshl_add_u32 v134, v4, 13, v6
	v_ashrrev_i32_e32 v4, 31, v2
	s_add_u32 s33, s2, 0x6c00000
	v_lshrrev_b32_e32 v4, 26, v4
	s_addc_u32 s46, s3, 0
	v_add_u32_e32 v4, v2, v4
	s_add_u32 s47, s2, 0x2700000
	v_lshlrev_b32_e32 v3, 3, v150
	v_ashrrev_i32_e32 v151, 6, v4
	v_and_b32_e32 v4, 0xc0, v4
	s_addc_u32 s48, s3, 0
	s_ashr_i32 s4, s6, 6
	v_and_b32_e32 v3, -16, v3
	v_sub_u32_e32 v2, v2, v4
	s_and_b32 s49, s4, 3
	v_add_u32_e32 v3, v151, v3
	v_ashrrev_i16_sdwa v2, v5, sext(v2) dst_sel:DWORD dst_unused:UNUSED_PAD src0_sel:DWORD src1_sel:BYTE_0
	v_and_b32_e32 v5, 3, v151
	s_ashr_i32 s7, s6, 8
	s_ashr_i32 s39, s38, 31
	s_ashr_i32 s19, s18, 31
	v_and_or_b32 v5, v3, s5, v5
	s_lshl_b32 s50, s4, 10
	s_lshl_b32 s5, s7, 6
	s_lshl_b32 s4, s49, 5
	s_lshl_b64 s[8:9], s[38:39], 21
	s_lshl_b64 s[10:11], s[18:19], 21
	s_add_u32 s40, s47, s10
	v_lshlrev_b32_e32 v6, 5, v150
	v_bfe_i32 v152, v2, 0, 16
	v_lshlrev_b32_e32 v2, 1, v3
	v_lshrrev_b32_e32 v4, 2, v3
	s_addc_u32 s41, s48, s11
	s_add_i32 s51, s50, 0
	v_and_b32_e32 v6, 32, v6
	v_and_b32_e32 v2, 24, v2
	v_and_b32_e32 v4, 4, v4
	s_add_i32 m0, s51, 0x10000
	v_or3_b32 v2, v5, v4, v2
	v_add_lshl_u32 v4, v6, v152, 1
	global_load_lds_dwordx4 v136, s[40:41]
	s_add_i32 m0, s51, 0x12000
	v_lshl_add_u32 v140, v2, 13, v4
	s_add_u32 s10, s40, 0x100000
	global_load_lds_dwordx4 v140, s[40:41]
	s_addc_u32 s11, s41, 0
	s_add_i32 m0, s51, 0x14000
	v_lshl_add_u32 v138, v3, 13, v4
	global_load_lds_dwordx4 v136, s[10:11]
	s_add_i32 m0, s51, 0x16000
	s_add_u32 s42, s33, s8
	s_addc_u32 s43, s46, s9
	s_add_i32 s52, s51, 0x2000
	global_load_lds_dwordx4 v140, s[10:11]
	s_mov_b32 m0, s51
	s_add_u32 s8, s42, 0x100000
	global_load_lds_dwordx4 v134, s[42:43]
	s_mov_b32 m0, s52
	s_addc_u32 s9, s43, 0
	s_add_i32 s53, s51, 0x4000
	global_load_lds_dwordx4 v138, s[42:43]
	s_mov_b32 m0, s53
	s_add_i32 s54, s51, 0x6000
	global_load_lds_dwordx4 v134, s[8:9]
	s_mov_b32 m0, s54
	v_and_b32_e32 v154, 15, v1
	global_load_lds_dwordx4 v138, s[8:9]
	s_lshl_b32 s8, s38, 8
	s_add_i32 s8, s8, s5
	v_bfe_u32 v148, v1, 4, 2
	v_or_b32_e32 v2, s8, v154
	s_lshl_b32 s8, s18, 8
	v_lshlrev_b32_e32 v153, 3, v148
	s_or_b32 s8, s8, s4
	v_or_b32_e32 v4, s8, v153
	v_or_b32_e32 v8, 16, v2
	v_ashrrev_i32_e32 v5, 31, v4
	v_ashrrev_i32_e32 v3, 31, v2
	v_ashrrev_i32_e32 v9, 31, v8
	v_lshl_add_u64 v[4:5], v[4:5], 1, s[0:1]
	v_lshlrev_b64 v[6:7], 11, v[2:3]
	v_lshlrev_b64 v[8:9], 11, v[8:9]
	v_lshl_add_u64 v[6:7], v[4:5], 0, v[6:7]
	v_lshl_add_u64 v[8:9], v[4:5], 0, v[8:9]
	flat_load_dwordx4 v[62:65], v[6:7]
	flat_load_dwordx4 v[58:61], v[6:7] offset:256
	flat_load_dwordx4 v[54:57], v[8:9]
	flat_load_dwordx4 v[46:49], v[8:9] offset:256
	v_or_b32_e32 v8, 32, v2
	v_or_b32_e32 v2, 48, v2
	v_ashrrev_i32_e32 v9, 31, v8
	v_ashrrev_i32_e32 v3, 31, v2
	v_lshlrev_b64 v[8:9], 11, v[8:9]
	v_lshlrev_b64 v[2:3], 11, v[2:3]
	s_mov_b32 s55, 0x40000
	v_lshl_add_u64 v[8:9], v[4:5], 0, v[8:9]
	v_lshl_add_u64 v[2:3], v[4:5], 0, v[2:3]
	v_add_co_u32_e32 v4, vcc, s55, v6
	s_mov_b64 s[8:9], 0x40000
	s_nop 0
	v_addc_co_u32_e32 v5, vcc, 0, v7, vcc
	s_mov_b32 s56, 0x48000
	flat_load_dwordx4 v[50:53], v[8:9]
	flat_load_dwordx4 v[38:41], v[8:9] offset:256
	flat_load_dwordx4 v[42:45], v[2:3]
	flat_load_dwordx4 v[26:29], v[2:3] offset:256
	v_lshl_add_u64 v[2:3], v[6:7], 0, s[8:9]
	flat_load_dwordx4 v[34:37], v[4:5]
	flat_load_dwordx4 v[18:21], v[2:3] offset:256
	v_add_co_u32_e32 v4, vcc, s56, v6
	s_mov_b64 s[10:11], 0x48000
	s_nop 0
	v_addc_co_u32_e32 v5, vcc, 0, v7, vcc
	s_mov_b32 s14, 0x50000
	v_lshl_add_u64 v[2:3], v[6:7], 0, s[10:11]
	flat_load_dwordx4 v[30:33], v[4:5]
	flat_load_dwordx4 v[10:13], v[2:3] offset:256
	v_add_co_u32_e32 v4, vcc, s14, v6
	s_mov_b64 s[12:13], 0x50000
	s_nop 0
	v_addc_co_u32_e32 v5, vcc, 0, v7, vcc
	s_mov_b64 s[14:15], 0x58000
	s_mov_b32 s16, 0x58000
	v_lshl_add_u64 v[2:3], v[6:7], 0, s[12:13]
	v_lshl_add_u64 v[14:15], v[6:7], 0, s[14:15]
	v_add_co_u32_e32 v6, vcc, s16, v6
	flat_load_dwordx4 v[22:25], v[4:5]
	s_nop 0
	flat_load_dwordx4 v[2:5], v[2:3] offset:256
	v_addc_co_u32_e32 v7, vcc, 0, v7, vcc
	flat_load_dwordx4 v[6:9], v[6:7]
	s_nop 0
	flat_load_dwordx4 v[14:17], v[14:15] offset:256
	v_mov_b32_e32 v137, 0
	v_mov_b32_e32 v141, v137
	v_mov_b32_e32 v135, v137
	v_mov_b32_e32 v139, v137
	s_cmp_eq_u32 s7, 1
	v_lshl_add_u64 v[144:145], s[40:41], 0, v[136:137]
	v_lshl_add_u64 v[142:143], s[40:41], 0, v[140:141]
	v_lshl_add_u64 v[132:133], s[42:43], 0, v[134:135]
	v_lshl_add_u64 v[130:131], s[42:43], 0, v[138:139]
	s_cselect_b64 s[16:17], -1, 0
	s_cmp_lg_u32 s7, 1
	s_mov_b32 s19, 0
	s_waitcnt vmcnt(0)
	s_cbranch_scc1 .LBB0_1029
	s_barrier

.LBB0_1295:
	s_andn2_b64 vcc, exec, s[0:1]
	s_cbranch_vccnz .LBB0_1395
	v_ashrrev_i32_e32 v3, 31, v1
	v_lshrrev_b32_e32 v3, 26, v3
	v_add_u32_e32 v3, v1, v3
	v_ashrrev_i32_e32 v12, 6, v3
	v_bfe_i32 v3, v1, 27, 1
	v_lshlrev_b32_e32 v2, 4, v1
	v_lshrrev_b32_e32 v3, 22, v3
	v_add_u32_e32 v3, v2, v3
	v_and_b32_e32 v3, 0xfffffc00, v3
	v_sub_u32_e32 v3, v2, v3
	v_lshrrev_b32_e32 v4, 4, v3
	v_bitop3_b32 v3, v4, v3, 32 bitop3:0x6c
	v_ashrrev_i32_e32 v5, 31, v3
	v_lshrrev_b32_e32 v5, 26, v5
	v_add_u32_e32 v5, v3, v5
	v_lshlrev_b32_e32 v4, 3, v12
	v_ashrrev_i32_e32 v13, 6, v5
	v_and_b32_e32 v5, 0xc0, v5
	v_and_b32_e32 v4, -16, v4
	v_sub_u32_e32 v3, v3, v5
	v_mov_b32_e32 v5, 1
	v_add_u32_e32 v4, v13, v4
	v_ashrrev_i16_sdwa v3, v5, sext(v3) dst_sel:DWORD dst_unused:UNUSED_PAD src0_sel:DWORD src1_sel:BYTE_0
	v_lshlrev_b32_e32 v6, 5, v12
	v_bfe_i32 v15, v3, 0, 16
	v_lshlrev_b32_e32 v3, 1, v4
	v_lshrrev_b32_e32 v7, 2, v4
	v_and_b32_e32 v8, 3, v13
	s_mov_b32 s5, 0x1fffe0
	v_and_b32_e32 v6, 32, v6
	v_and_b32_e32 v3, 24, v3
	v_and_b32_e32 v7, 4, v7
	v_and_or_b32 v8, v4, s5, v8
	v_or3_b32 v3, v8, v7, v3
	v_add_lshl_u32 v6, v6, v15, 1
	v_add_u32_e32 v2, 0x2000, v2
	v_lshl_add_u32 v156, v3, 11, v6
	v_ashrrev_i32_e32 v3, 31, v2
	v_lshrrev_b32_e32 v3, 22, v3
	v_add_u32_e32 v3, v2, v3
	v_ashrrev_i32_e32 v16, 10, v3
	v_mul_i32_i24_e32 v3, 0x400, v16
	v_sub_u32_e32 v2, v2, v3
	v_lshrrev_b32_e32 v3, 4, v2
	v_bitop3_b32 v2, v3, v2, 32 bitop3:0x6c
	v_lshl_add_u32 v154, v4, 11, v6
	v_ashrrev_i32_e32 v4, 31, v2
	v_lshrrev_b32_e32 v4, 26, v4
	s_add_u32 s0, s2, 0x4c00000
	v_add_u32_e32 v4, v2, v4
	s_addc_u32 s1, s3, 0
	v_lshlrev_b32_e32 v3, 3, v16
	v_ashrrev_i32_e32 v17, 6, v4
	v_and_b32_e32 v4, 0xc0, v4
	s_add_u32 s42, s2, 0x3700000
	v_and_b32_e32 v3, -16, v3
	v_sub_u32_e32 v2, v2, v4
	s_addc_u32 s43, s3, 0
	s_ashr_i32 s4, s6, 6
	v_add_u32_e32 v3, v17, v3
	v_ashrrev_i16_sdwa v2, v5, sext(v2) dst_sel:DWORD dst_unused:UNUSED_PAD src0_sel:DWORD src1_sel:BYTE_0
	v_and_b32_e32 v5, 3, v17
	s_ashr_i32 s7, s6, 8
	s_ashr_i32 s35, s34, 31
	s_ashr_i32 s11, s10, 31
	v_and_or_b32 v5, v3, s5, v5
	s_lshl_b32 s44, s4, 10
	s_lshl_b32 s5, s7, 6
	s_lshl_b64 s[8:9], s[34:35], 19
	s_lshl_b64 s[12:13], s[10:11], 19
	s_add_u32 s36, s42, s12
	v_lshlrev_b32_e32 v6, 5, v16
	v_bfe_i32 v18, v2, 0, 16
	v_lshlrev_b32_e32 v2, 1, v3
	v_lshrrev_b32_e32 v4, 2, v3
	s_addc_u32 s37, s43, s13
	s_add_i32 s45, s44, 0
	v_and_b32_e32 v6, 32, v6
	v_and_b32_e32 v2, 24, v2
	v_and_b32_e32 v4, 4, v4
	s_add_i32 m0, s45, 0x10000
	v_or3_b32 v2, v5, v4, v2
	v_add_lshl_u32 v4, v6, v18, 1
	global_load_lds_dwordx4 v156, s[36:37]
	s_add_i32 m0, s45, 0x12000
	v_lshl_add_u32 v160, v2, 11, v4
	s_add_u32 s12, s36, 0x40000
	global_load_lds_dwordx4 v160, s[36:37]
	s_addc_u32 s13, s37, 0
	s_add_i32 m0, s45, 0x14000
	v_lshl_add_u32 v158, v3, 11, v4
	global_load_lds_dwordx4 v156, s[12:13]
	s_add_i32 m0, s45, 0x16000
	s_add_u32 s38, s0, s8
	s_addc_u32 s39, s1, s9
	s_add_i32 s46, s45, 0x2000
	global_load_lds_dwordx4 v160, s[12:13]
	s_mov_b32 m0, s45
	s_add_u32 s8, s38, 0x40000
	global_load_lds_dwordx4 v154, s[38:39]
	s_mov_b32 m0, s46
	s_addc_u32 s9, s39, 0
	s_add_i32 s47, s45, 0x4000
	global_load_lds_dwordx4 v158, s[38:39]
	s_mov_b32 m0, s47
	s_add_i32 s48, s45, 0x6000
	global_load_lds_dwordx4 v154, s[8:9]
	s_mov_b32 m0, s48
	v_and_b32_e32 v19, 15, v1
	global_load_lds_dwordx4 v158, s[8:9]
	s_lshl_b32 s8, s34, 8
	s_add_i32 s8, s8, s5
	v_bfe_u32 v14, v1, 4, 2
	v_mov_b32_e32 v157, 0
	v_or_b32_e32 v4, s8, v19
	v_lshlrev_b32_e32 v2, 4, v14
	v_mov_b32_e32 v3, v157
	v_or_b32_e32 v8, 16, v4
	v_lshl_add_u64 v[6:7], s[2:3], 0, v[2:3]
	s_mov_b64 s[8:9], 0x400000
	v_ashrrev_i32_e32 v5, 31, v4
	v_ashrrev_i32_e32 v9, 31, v8
	v_lshl_add_u64 v[162:163], v[6:7], 0, s[8:9]
	v_lshlrev_b64 v[6:7], 6, v[4:5]
	v_lshlrev_b64 v[8:9], 6, v[8:9]
	v_lshl_add_u64 v[6:7], v[162:163], 0, v[6:7]
	v_lshl_add_u64 v[8:9], v[162:163], 0, v[8:9]
	flat_load_dwordx4 v[20:23], v[6:7]
	flat_load_dwordx4 v[24:27], v[8:9]
	v_or_b32_e32 v8, 32, v4
	v_or_b32_e32 v4, 48, v4
	v_ashrrev_i32_e32 v5, 31, v4
	v_ashrrev_i32_e32 v9, 31, v8
	v_lshlrev_b64 v[4:5], 6, v[4:5]
	v_lshlrev_b64 v[8:9], 6, v[8:9]
	v_lshl_add_u64 v[4:5], v[162:163], 0, v[4:5]
	v_lshl_add_u64 v[8:9], v[162:163], 0, v[8:9]
	flat_load_dwordx4 v[32:35], v[4:5]
	s_movk_i32 s49, 0x2000
	flat_load_dwordx4 v[28:31], v[8:9]
	v_add_co_u32_e32 v4, vcc, s49, v6
	v_mbcnt_lo_u32_b32 v1, -1, 0
	s_nop 0
	v_addc_co_u32_e32 v5, vcc, 0, v7, vcc
	flat_load_dwordx4 v[36:39], v[4:5]
	flat_load_dwordx4 v[40:43], v[4:5] offset:1024
	flat_load_dwordx4 v[44:47], v[4:5] offset:2048
	flat_load_dwordx4 v[48:51], v[4:5] offset:3072
	v_mbcnt_hi_u32_b32 v3, -1, v1
	v_and_b32_e32 v52, 64, v3
	v_xor_b32_e32 v1, 16, v3
	v_add_u32_e32 v52, 64, v52
	v_cmp_lt_i32_e32 vcc, v1, v52
	v_xor_b32_e32 v53, 32, v3
	v_mov_b32_e32 v161, v157
	v_cndmask_b32_e32 v1, v3, v1, vcc
	v_lshlrev_b32_e32 v1, 2, v1
	v_cmp_lt_i32_e32 vcc, v53, v52
	v_mov_b32_e32 v155, v157
	v_mov_b32_e32 v159, v157
	v_cndmask_b32_e32 v3, v3, v53, vcc
	v_lshlrev_b32_e32 v179, 2, v3
	s_cmp_eq_u32 s7, 1
	v_lshl_add_u64 v[10:11], s[36:37], 0, v[156:157]
	v_lshl_add_u64 v[8:9], s[36:37], 0, v[160:161]
	v_lshl_add_u64 v[6:7], s[38:39], 0, v[154:155]
	v_lshl_add_u64 v[4:5], s[38:39], 0, v[158:159]
	s_cselect_b64 s[8:9], -1, 0
	s_cmp_lg_u32 s7, 1
	s_mov_b32 s11, 0
	s_waitcnt lgkmcnt(0)
	s_waitcnt vmcnt(0)
	v_add_f32_e32 v20, v20, v21
	v_add_f32_e32 v21, v22, v23
	s_waitcnt vmcnt(0)
	v_add_f32_e32 v22, v24, v25
	v_add_f32_e32 v23, v26, v27
	v_add_f32_e32 v23, v22, v23
	ds_bpermute_b32 v24, v1, v23
	v_add_f32_e32 v20, v20, v21
	ds_bpermute_b32 v21, v1, v20
	v_add_f32_e32 v25, v32, v33
	v_add_f32_e32 v26, v34, v35
	s_waitcnt lgkmcnt(1)
	v_add_f32_e32 v3, v23, v24
	v_add_f32_e32 v23, v28, v29
	v_add_f32_e32 v24, v30, v31
	v_add_f32_e32 v25, v25, v26
	v_add_f32_e32 v26, v36, v37
	v_add_f32_e32 v28, v38, v39
	v_add_f32_e32 v23, v23, v24
	v_add_f32_e32 v29, v26, v28
	ds_bpermute_b32 v24, v1, v23
	ds_bpermute_b32 v30, v1, v29
	v_add_f32_e32 v31, v44, v45
	v_add_f32_e32 v32, v46, v47
	v_add_f32_e32 v31, v31, v32
	s_waitcnt lgkmcnt(1)
	v_add_f32_e32 v26, v23, v24
	s_waitcnt lgkmcnt(0)
	v_add_f32_e32 v23, v29, v30
	v_add_f32_e32 v29, v40, v41
	v_add_f32_e32 v30, v42, v43
	v_add_f32_e32 v32, v48, v49
	v_add_f32_e32 v34, v50, v51
	v_add_f32_e32 v29, v29, v30
	v_add_f32_e32 v35, v32, v34
	ds_bpermute_b32 v27, v1, v25
	ds_bpermute_b32 v30, v1, v29
	ds_bpermute_b32 v33, v1, v31
	ds_bpermute_b32 v36, v1, v35
	v_add_f32_e32 v21, v20, v21
	s_waitcnt lgkmcnt(3)
	v_add_f32_e32 v24, v25, v27
	s_waitcnt lgkmcnt(2)
	v_add_f32_e32 v32, v29, v30
	s_waitcnt lgkmcnt(1)
	v_add_f32_e32 v30, v31, v33
	s_waitcnt lgkmcnt(0)
	v_add_f32_e32 v29, v35, v36
	ds_bpermute_b32 v22, v179, v21
	ds_bpermute_b32 v20, v179, v3
	ds_bpermute_b32 v28, v179, v26
	ds_bpermute_b32 v27, v179, v24
	ds_bpermute_b32 v25, v179, v23
	ds_bpermute_b32 v34, v179, v32
	ds_bpermute_b32 v33, v179, v30
	ds_bpermute_b32 v31, v179, v29
	s_cbranch_scc1 .LBB0_1298
	s_barrier
